# experiment: only the 16-byte global stores inside the layer loop marked sc1 (write-through)
# speedup vs baseline: 1.0184x; 1.0184x over previous
; #define LAS __attribute__((address_space(3)))
; DI float ex2(float x) { return __builtin_amdgcn_exp2f(x); }
; DI float a_bound(const bf16x8 (&qf)[2], const float* kmax_l, int b, int h) { return sqrtf(q_norm2(qf) * (kmax_l[b * 128 + 8 + 2 * h] + kmax_l[b * 128 + 9 + 2 * h])) * 1.01f + 0.05f; }
; DI void tile_load(TileRegs& R, const bf16* kb, const bf16* vb, int tokbase, int stride, int lane) {
; #pragma unroll
;     for (int it = 0; it < 4; ++it) { const int n = lane + 64 * it, row = n >> 3, ch = n & 7; int tok = tokbase + stride * row; tok = min(max(tok, 0), T - 1);
;         R.k[it] = *(const u32x4*)(kb + (size_t)tok * 64 + ch * 8); R.v[it] = *(const u32x4*)(vb + (size_t)tok * 64 + ch * 8); }
; }
; DI void mixerA1_unit(int u, const bf16* PROJ, bf16* YC, float* LPA, const float* kmax_l, LAS char* vt, int wave, int lane) {
;     const int b = u >> 6, h = (u >> 4) & 3, qblk = u & 15, r = lane & 15, g = lane >> 4;
;     const bf16* kb = slab(PROJ, C_AK + h * 64, b); const bf16* vb = slab(PROJ, C_AV + h * 64, b);
;     const int t0 = qblk * 128 + wave * 16, tq = t0 + r;
;     bf16x8 qf[2];
; #pragma unroll
;     for (int ks = 0; ks < 2; ++ks) qf[ks] = *(const bf16x8*)(slab(PROJ, C_AQ + h * 64, b) + (size_t)tq * 64 + 32 * ks + 8 * g);
;     const float nslope2 = -ex2(-(float)(2 * h + 1)) * LOG2E;
;     const float bound = a_bound(qf, kmax_l, b, h);
;     const f32x4 cinit = {-bound, -bound, -bound, -bound};
;     f32x4 o[4], ol = {0.f, 0.f, 0.f, 0.f};
; #pragma unroll
;     for (int c = 0; c < 4; ++c) o[c] = ol;
;     TileRegs R0, R1, R2;
;     const int tb0 = t0 - 64;
;     tile_load(R0, kb, vb, tb0, 1, lane); tile_load(R1, kb, vb, tb0 + 32, 1, lane); tile_load(R2, kb, vb, tb0 + 64, 1, lane);
;     f32x4 sA[2], sB[2];
.LBB0_359:
	s_ashr_i32 s20, s26, 6
	s_bfe_u32 s27, s26, 0x20004
	s_ashr_i32 s21, s20, 31
	s_lshl_b32 s0, s27, 21
	s_add_u32 s31, s10, s0
	s_addc_u32 s33, s11, 0
	s_and_b32 s30, s16, 0x780
	s_add_i32 s30, s30, s5
	s_lshl_b64 s[0:1], s[20:21], 18
	v_or_b32_e32 v114, s30, v109
	s_add_u32 s0, s31, s0
	v_ashrrev_i32_e32 v115, 31, v114
	s_addc_u32 s1, s33, s1
	v_lshlrev_b64 v[4:5], 7, v[114:115]
	v_lshl_add_u64 v[4:5], s[0:1], 0, v[4:5]
	v_lshlrev_b32_e32 v188, 1, v108
	v_lshl_add_u64 v[8:9], v[4:5], 0, v[188:189]
	global_load_dwordx4 v[4:7], v[8:9], off offset:64
	s_nop 0
	global_load_dwordx4 v[8:11], v[8:9], off
	s_lshl_b32 s31, s27, 1
	s_lshl_b32 s33, s20, 7
	s_or_b32 s38, s31, s33
	s_ashr_i32 s39, s38, 31
	s_or_b32 s34, s31, 1
	s_lshl_b64 s[38:39], s[38:39], 2
	s_add_u32 s38, s2, s38
	s_addc_u32 s39, s4, s39
	global_load_dwordx2 v[12:13], v189, s[38:39] offset:32
	v_mov_b32_e32 v111, v189
	v_lshl_add_u64 v[14:15], s[0:1], 0, v[110:111]
	s_mov_b64 s[0:1], 0x800000
	v_lshl_add_u64 v[120:121], v[14:15], 0, s[0:1]
	s_mov_b64 s[0:1], 0x1000000
	s_sub_i32 s33, s30, 64
	v_lshl_add_u64 v[122:123], v[14:15], 0, s[0:1]
	v_or_b32_e32 v14, s33, v126
	v_cvt_f32_ubyte0_e32 v16, s34
	v_or_b32_e32 v15, s33, v127
	v_med3_i32 v14, v14, 0, v233
	v_exp_f32_e64 v34, -v16
	v_add_u32_e32 v16, s33, v128
	v_med3_i32 v18, v15, 0, v233
	v_lshlrev_b32_e32 v188, 7, v14
	v_add_u32_e32 v17, s33, v129
	v_med3_i32 v22, v16, 0, v233
	v_lshl_add_u64 v[14:15], v[120:121], 0, v[188:189]
	v_lshl_add_u64 v[20:21], v[122:123], 0, v[188:189]
	v_lshlrev_b32_e32 v188, 7, v18
	v_med3_i32 v23, v17, 0, v233
	global_load_dwordx4 v[16:19], v[14:15], off
	global_load_dwordx4 v[36:39], v[20:21], off
	v_lshl_add_u64 v[14:15], v[120:121], 0, v[188:189]
	v_lshl_add_u64 v[20:21], v[122:123], 0, v[188:189]
	v_lshlrev_b32_e32 v188, 7, v22
	global_load_dwordx4 v[40:43], v[14:15], off
	global_load_dwordx4 v[44:47], v[20:21], off
	v_lshl_add_u64 v[14:15], v[120:121], 0, v[188:189]
	v_lshl_add_u64 v[20:21], v[122:123], 0, v[188:189]
	global_load_dwordx4 v[48:51], v[14:15], off
	global_load_dwordx4 v[52:55], v[20:21], off
	v_lshlrev_b32_e32 v188, 7, v23
	s_sub_i32 s31, s30, 32
	v_or_b32_e32 v35, s31, v126
	v_or_b32_e32 v116, s30, v126
	v_or_b32_e32 v118, s30, v127
	v_mul_f32_e32 v111, 0xbfb8aa3b, v34
	v_add_u32_e32 v64, s30, v128
	v_med3_i32 v64, v64, 0, v233
	s_cmpk_lt_u32 s33, 0x800
	s_waitcnt vmcnt(8)
	v_and_b32_e32 v21, 0xffff0000, v4
	s_waitcnt vmcnt(7)
	v_and_b32_e32 v20, 0xffff0000, v8
	v_and_b32_e32 v25, 0xffff0000, v5
	v_and_b32_e32 v24, 0xffff0000, v9
	v_lshlrev_b32_e32 v15, 16, v4
	v_lshlrev_b32_e32 v14, 16, v8
	v_lshlrev_b32_e32 v23, 16, v5
	v_lshlrev_b32_e32 v22, 16, v9
	v_and_b32_e32 v29, 0xffff0000, v6
	v_and_b32_e32 v28, 0xffff0000, v10
	v_pk_mul_f32 v[20:21], v[20:21], v[20:21]
	v_pk_mul_f32 v[24:25], v[24:25], v[24:25]
	v_lshlrev_b32_e32 v27, 16, v6
	v_lshlrev_b32_e32 v26, 16, v10
	v_and_b32_e32 v33, 0xffff0000, v7
	v_and_b32_e32 v32, 0xffff0000, v11
	v_pk_mul_f32 v[28:29], v[28:29], v[28:29]
	v_pk_fma_f32 v[14:15], v[14:15], v[14:15], v[20:21]
	v_pk_fma_f32 v[20:21], v[22:23], v[22:23], v[24:25]
	v_lshlrev_b32_e32 v31, 16, v7
	v_lshlrev_b32_e32 v30, 16, v11
	v_pk_mul_f32 v[32:33], v[32:33], v[32:33]
	v_pk_fma_f32 v[22:23], v[26:27], v[26:27], v[28:29]
	v_pk_add_f32 v[14:15], v[14:15], v[20:21]
	v_pk_fma_f32 v[24:25], v[30:31], v[30:31], v[32:33]
	v_pk_add_f32 v[14:15], v[22:23], v[14:15]
	v_lshl_add_u64 v[20:21], v[122:123], 0, v[188:189]
	v_pk_add_f32 v[14:15], v[24:25], v[14:15]
	v_med3_i32 v28, v118, 0, v233
	v_add_f32_e32 v22, v14, v15
	v_lshl_add_u64 v[14:15], v[120:121], 0, v[188:189]
	global_load_dwordx4 v[56:59], v[14:15], off
	global_load_dwordx4 v[60:63], v[20:21], off
	ds_bpermute_b32 v23, v124, v22
	s_waitcnt vmcnt(8)
	v_mov_b32_e32 v14, v12
	v_mov_b32_e32 v20, v13
	s_waitcnt lgkmcnt(0)
	v_add_f32_e32 v15, v22, v23
	ds_bpermute_b32 v21, v125, v15
	v_med3_i32 v22, v35, 0, v233
	v_lshlrev_b32_e32 v188, 7, v22
	v_lshl_add_u64 v[22:23], v[122:123], 0, v[188:189]
	s_waitcnt lgkmcnt(0)
	v_pk_add_f32 v[12:13], v[14:15], v[20:21]
	v_lshl_add_u64 v[20:21], v[120:121], 0, v[188:189]
	global_load_dwordx4 v[84:87], v[20:21], off
	global_load_dwordx4 v[88:91], v[22:23], off
	v_or_b32_e32 v20, s31, v127
	v_med3_i32 v20, v20, 0, v233
	v_lshlrev_b32_e32 v188, 7, v20
	v_lshl_add_u64 v[20:21], v[120:121], 0, v[188:189]
	v_lshl_add_u64 v[22:23], v[122:123], 0, v[188:189]
	global_load_dwordx4 v[92:95], v[20:21], off
	global_load_dwordx4 v[96:99], v[22:23], off
	v_add_u32_e32 v20, s31, v128
	v_med3_i32 v20, v20, 0, v233
	v_lshlrev_b32_e32 v188, 7, v20
	v_lshl_add_u64 v[20:21], v[120:121], 0, v[188:189]
	v_lshl_add_u64 v[22:23], v[122:123], 0, v[188:189]
	global_load_dwordx4 v[100:103], v[20:21], off
	global_load_dwordx4 v[104:107], v[22:23], off
	v_add_u32_e32 v20, s31, v129
	v_med3_i32 v20, v20, 0, v233
	v_lshlrev_b32_e32 v188, 7, v20
	v_lshl_add_u64 v[20:21], v[120:121], 0, v[188:189]
	v_lshl_add_u64 v[22:23], v[122:123], 0, v[188:189]
	global_load_dwordx4 v[146:149], v[20:21], off
	global_load_dwordx4 v[150:153], v[22:23], off
	v_mul_f32_e32 v12, v12, v13
	v_mul_f32_e32 v13, 0x4f800000, v12
	v_cmp_gt_f32_e64 s[0:1], s92, v12
	v_med3_i32 v20, v116, 0, v233
	v_lshlrev_b32_e32 v188, 7, v20
	v_cndmask_b32_e64 v12, v12, v13, s[0:1]
	v_sqrt_f32_e32 v13, v12
	v_lshl_add_u64 v[20:21], v[120:121], 0, v[188:189]
	v_add_u32_e32 v14, -1, v13
	v_add_u32_e32 v15, 1, v13
	v_fma_f32 v24, -v14, v13, v12
	v_fma_f32 v25, -v15, v13, v12
	v_cmp_ge_f32_e64 s[38:39], 0, v24
	s_nop 1
	v_cndmask_b32_e64 v13, v13, v14, s[38:39]
	v_cmp_lt_f32_e64 s[38:39], 0, v25
	v_lshl_add_u64 v[24:25], v[122:123], 0, v[188:189]
	v_lshlrev_b32_e32 v188, 7, v28
	v_lshl_add_u64 v[28:29], v[120:121], 0, v[188:189]
	v_lshl_add_u64 v[32:33], v[122:123], 0, v[188:189]
	global_load_dwordx4 v[20:23], v[20:21], off
	s_nop 0
	global_load_dwordx4 v[24:27], v[24:25], off
	s_nop 0
	global_load_dwordx4 v[28:31], v[28:29], off
	s_nop 0
	global_load_dwordx4 v[32:35], v[32:33], off
	s_waitcnt vmcnt(18)
; #define LAS __attribute__((address_space(3)))
; #define MFMA16(a, b, c) __builtin_amdgcn_mfma_f32_16x16x32_bf16((a), (b), (c), 0, 0, 0)
; template <bool EDGE>
; DI void a_scores(f32x4 (&st)[2], const LAS char* kt, const bf16x8 (&qf)[2], const f32x4 cinit, int tokbase, int stride, int maxd, int tq, float nslope2, int lane) {
;     const int g = lane >> 4;
;     const int base0 = tokbase + stride * 4 * g - tq;
; #pragma unroll
;     for (int t = 0; t < 2; ++t) {
;         st[t] = MFMA16(k_frag_at(kt, t, 0, lane), qf[0], cinit); st[t] = MFMA16(k_frag_at(kt, t, 1, lane), qf[1], st[t]);
; #pragma unroll
;         for (int i = 0; i < 4; ++i) { const int d = base0 + stride * (16 * t + i);
;             bool ok = (unsigned)(d + maxd) <= (unsigned)(2 * maxd);
;             if (EDGE) ok = ok && ((unsigned)(d + tq) < (unsigned)T);
;             const float v = __builtin_fmaf(__builtin_fabsf((float)d), nslope2, st[t][i]);
;             st[t][i] = ok ? v : -1e30f; }
;     }
; }
; DI void a_stage(f32x4 (&st)[2], const TileRegs& R, LAS char* vt, int vpar, const bf16x8 (&qf)[2], const f32x4 cinit, int tokbase, int stride, int maxd, int tq, float nslope2, int lane) {
; #pragma unroll
;     for (int it = 0; it < 4; ++it) { const int n = lane + 64 * it, row = n >> 3, ch = n & 7;
;         *(LAS u32x4*)(vt + vpar * A_V1 + row * VT_PITCH + ch * 16) = R.v[it]; *(LAS u32x4*)(vt + A_K + row * VT_PITCH + ch * 16) = R.k[it]; }
;     a_scores<true>(st, vt + A_K, qf, cinit, tokbase, stride, maxd, tq, nslope2, lane);
; }
; DI void mixerA1_unit(int u, const bf16* PROJ, bf16* YC, float* LPA, const float* kmax_l, LAS char* vt, int wave, int lane) {
;     ...
;     const float bound = a_bound(qf, kmax_l, b, h);
;     const f32x4 cinit = {-bound, -bound, -bound, -bound};
;     f32x4 o[4], ol = {0.f, 0.f, 0.f, 0.f};
; #pragma unroll
;     for (int c = 0; c < 4; ++c) o[c] = ol;
;     TileRegs R0, R1, R2;
;     const int tb0 = t0 - 64;
;     tile_load(R0, kb, vb, tb0, 1, lane); tile_load(R1, kb, vb, tb0 + 32, 1, lane); tile_load(R2, kb, vb, tb0 + 64, 1, lane);
;     f32x4 sA[2], sB[2];
;     a_stage(sA, R0, vt, 0, qf, cinit, tb0, 1, 64, tq, nslope2, lane);        tile_load(R0, kb, vb, tb0 + 96, 1, lane);
;     a_stage(sB, R1, vt, 1, qf, cinit, tb0 + 32, 1, 64, tq, nslope2, lane);   tile_load(R1, kb, vb, tb0 + 128, 1, lane);
	ds_write_b128 v142, v[36:39]
	ds_write_b128 v142, v[16:19] offset:9216
	s_waitcnt vmcnt(16)
	ds_write_b128 v142, v[44:47] offset:1152
	ds_write_b128 v142, v[40:43] offset:10368
	s_waitcnt vmcnt(14)
	ds_write_b128 v142, v[52:55] offset:2304
	ds_write_b128 v142, v[48:51] offset:11520
	s_waitcnt vmcnt(12)
	ds_write_b128 v142, v[60:63] offset:3456
	ds_write_b128 v142, v[56:59] offset:12672
	ds_read_b128 v[16:19], v143 offset:9216
	v_cndmask_b32_e64 v13, v13, v15, s[38:39]
	v_lshlrev_b32_e32 v188, 7, v64
	v_mul_f32_e32 v14, 0x37800000, v13
	v_lshl_add_u64 v[64:65], v[120:121], 0, v[188:189]
	v_add_u32_e32 v36, s30, v129
	v_cndmask_b32_e64 v13, v13, v14, s[0:1]
	v_cmp_class_f32_e64 s[0:1], v12, v226
	v_lshl_add_u64 v[66:67], v[122:123], 0, v[188:189]
	global_load_dwordx4 v[40:43], v[64:65], off
	global_load_dwordx4 v[48:51], v[66:67], off
	v_med3_i32 v44, v36, 0, v233
	ds_read_b128 v[36:39], v143 offset:9280
	v_cndmask_b32_e64 v12, v13, v12, s[0:1]
	v_fmamk_f32 v12, v12, 0x3f8147ae, v227
	v_xor_b32_e32 v12, 0x80000000, v12
	v_mov_b32_e32 v13, v12
	v_mov_b32_e32 v14, v12
	v_mov_b32_e32 v15, v12
	v_or_b32_e32 v52, s33, v131
	v_sub_u32_e32 v53, v52, v114
	s_waitcnt lgkmcnt(1)
	v_mfma_f32_16x16x32_bf16 v[16:19], v[16:19], v[8:11], v[12:15]
	s_cselect_b64 s[38:39], -1, 0
	v_lshlrev_b32_e32 v188, 7, v44
	v_lshl_add_u64 v[44:45], v[120:121], 0, v[188:189]
	s_waitcnt lgkmcnt(0)
	v_mfma_f32_16x16x32_bf16 v[16:19], v[36:39], v[4:7], v[16:19]
	v_cvt_f32_i32_e32 v37, v53
	v_add_u32_e32 v36, 64, v53
	v_cmp_gt_u32_e64 s[0:1], s73, v36
	v_add_u32_e32 v36, 1, v53
	v_cvt_f32_i32_e32 v36, v36
	s_nop 2
	v_fma_f32 v16, |v37|, v111, v16
	s_and_b64 s[0:1], s[38:39], s[0:1]
	v_cndmask_b32_e64 v113, v234, v16, s[0:1]
	v_add_u32_e32 v16, 0x41, v53
	v_cmp_gt_u32_e64 s[0:1], s73, v16
	v_lshl_add_u64 v[46:47], v[122:123], 0, v[188:189]
	global_load_dwordx4 v[56:59], v[44:45], off
	global_load_dwordx4 v[64:67], v[46:47], off
	v_fma_f32 v16, |v36|, v111, v17
	s_and_b64 s[0:1], s[38:39], s[0:1]
	ds_read_b128 v[36:39], v143 offset:11520
	ds_read_b128 v[44:47], v143 offset:11584
	v_cndmask_b32_e64 v115, v234, v16, s[0:1]
	v_add_u32_e32 v16, 2, v53
	v_cvt_f32_i32_e32 v16, v16
	v_add_u32_e32 v17, 0x42, v53
	v_cmp_gt_u32_e64 s[0:1], s73, v17
	s_and_b64 s[0:1], s[38:39], s[0:1]
	v_fma_f32 v16, |v16|, v111, v18
	v_cndmask_b32_e64 v117, v234, v16, s[0:1]
	v_add_u32_e32 v16, 3, v53
	v_cvt_f32_i32_e32 v16, v16
	s_waitcnt lgkmcnt(1)
	v_mfma_f32_16x16x32_bf16 v[36:39], v[36:39], v[8:11], v[12:15]
	v_add_u32_e32 v17, 0x43, v53
	v_cmp_gt_u32_e64 s[0:1], s73, v17
	v_fma_f32 v16, |v16|, v111, v19
	s_and_b64 s[0:1], s[38:39], s[0:1]
	v_cndmask_b32_e64 v119, v234, v16, s[0:1]
	s_waitcnt lgkmcnt(0)
	v_mfma_f32_16x16x32_bf16 v[16:19], v[44:47], v[4:7], v[36:39]
	s_sub_i32 s33, s30, 48
	s_cmpk_lt_u32 s33, 0x800
	s_cselect_b64 s[38:39], -1, 0
	v_add_u32_e32 v36, 16, v53
	v_cvt_f32_i32_e32 v36, v36
	v_add_u32_e32 v37, 0x50, v53
	v_cmp_gt_u32_e64 s[0:1], s73, v37
	s_and_b64 s[0:1], s[38:39], s[0:1]
	v_fma_f32 v16, |v36|, v111, v16
	v_cndmask_b32_e64 v154, v234, v16, s[0:1]
	v_add_u32_e32 v16, 17, v53
	v_cvt_f32_i32_e32 v16, v16
	v_add_u32_e32 v36, 0x51, v53
	v_cmp_gt_u32_e64 s[0:1], s73, v36
	v_add_u32_e32 v36, 17, v52
	v_cmp_gt_u32_e64 s[38:39], s24, v36
	v_fma_f32 v16, |v16|, v111, v17
	s_and_b64 s[0:1], s[0:1], s[38:39]
	v_cndmask_b32_e64 v155, v234, v16, s[0:1]
	v_add_u32_e32 v16, 18, v53
	v_cvt_f32_i32_e32 v16, v16
	v_add_u32_e32 v17, 0x52, v53
	v_cmp_gt_u32_e64 s[0:1], s73, v17
	v_add_u32_e32 v17, 18, v52
	v_cmp_gt_u32_e64 s[38:39], s24, v17
	v_fma_f32 v16, |v16|, v111, v18
	s_and_b64 s[0:1], s[0:1], s[38:39]
	v_cndmask_b32_e64 v156, v234, v16, s[0:1]
	v_add_u32_e32 v16, 19, v53
	v_cvt_f32_i32_e32 v16, v16
	v_add_u32_e32 v17, 0x53, v53
	v_cmp_gt_u32_e64 s[0:1], s73, v17
	v_add_u32_e32 v17, 19, v52
	v_cmp_gt_u32_e64 s[38:39], s24, v17
	v_fma_f32 v16, |v16|, v111, v19
	s_and_b64 s[0:1], s[0:1], s[38:39]
	s_add_i32 s33, s30, 32
	v_cndmask_b32_e64 v157, v234, v16, s[0:1]
	v_or_b32_e32 v16, s33, v126
	v_med3_i32 v16, v16, 0, v233
	v_lshlrev_b32_e32 v188, 7, v16
	v_lshl_add_u64 v[16:17], v[120:121], 0, v[188:189]
	v_lshl_add_u64 v[18:19], v[122:123], 0, v[188:189]
	global_load_dwordx4 v[68:71], v[16:17], off
	global_load_dwordx4 v[72:75], v[18:19], off
	v_or_b32_e32 v16, s33, v127
	v_med3_i32 v16, v16, 0, v233
	v_lshlrev_b32_e32 v188, 7, v16
	v_lshl_add_u64 v[16:17], v[120:121], 0, v[188:189]
	v_lshl_add_u64 v[18:19], v[122:123], 0, v[188:189]
	global_load_dwordx4 v[76:79], v[16:17], off
	global_load_dwordx4 v[80:83], v[18:19], off
	v_add_u32_e32 v16, s33, v128
	v_med3_i32 v16, v16, 0, v233
	s_waitcnt vmcnt(18)
	ds_write_b128 v142, v[88:91] offset:4608
	ds_write_b128 v142, v[84:87] offset:9216
	s_waitcnt vmcnt(16)
	ds_write_b128 v142, v[96:99] offset:5760
	ds_write_b128 v142, v[92:95] offset:10368
	s_waitcnt vmcnt(14)
	ds_write_b128 v142, v[104:107] offset:6912
	ds_write_b128 v142, v[100:103] offset:11520
	s_waitcnt vmcnt(12)
	ds_write_b128 v142, v[150:153] offset:8064
	ds_write_b128 v142, v[146:149] offset:12672
	v_lshlrev_b32_e32 v188, 7, v16
	ds_read_b128 v[16:19], v143 offset:9216
	v_lshl_add_u64 v[36:37], v[120:121], 0, v[188:189]
	v_lshl_add_u64 v[38:39], v[122:123], 0, v[188:189]
	global_load_dwordx4 v[84:87], v[36:37], off
	global_load_dwordx4 v[88:91], v[38:39], off
	v_add_u32_e32 v36, s33, v129
	v_med3_i32 v44, v36, 0, v233
	ds_read_b128 v[36:39], v143 offset:9280
	s_waitcnt lgkmcnt(1)
	v_mfma_f32_16x16x32_bf16 v[16:19], v[16:19], v[8:11], v[12:15]
	v_or_b32_e32 v52, s31, v131
	v_sub_u32_e32 v53, v52, v114
	s_cmpk_lt_u32 s31, 0x800
	s_waitcnt lgkmcnt(0)
; DI void fb_update(f32x4 (&o)[4], f32x4& ol, const f32x4 st0, const f32x4 st1, const LAS char* vt, int lane) {
;     f32x4 p0, p1;
; #pragma unroll
;     for (int i = 0; i < 4; ++i) { p0[i] = ex2(st0[i]); p1[i] = ex2(st1[i]); }
;     const bf16x8 pf = pack8(p0, p1);
;     const bf16x8 ones = {0x3F80, 0x3F80, 0x3F80, 0x3F80, 0x3F80, 0x3F80, 0x3F80, 0x3F80};
;     ol = MFMA16(ones, pf, ol);
;     const int g = lane >> 4, q = (lane & 15) >> 2, p = lane & 3;
;     const LAS char* v0 = vt + (4 * g + q) * VT_PITCH + 8 * p;
;     const LAS char* v1 = v0 + 16 * VT_PITCH;
; #pragma unroll
;     for (int c = 0; c < 4; ++c) { const bf16x8 vf = cat8(vtr(v0 + 32 * c), vtr(v1 + 32 * c)); o[c] = MFMA16(vf, pf, o[c]); }
; }
; DI float q_norm2(const bf16x8 (&qf)[2]) { float a = sumsq8(qf[0]) + sumsq8(qf[1]); a += __shfl_xor(a, 16); a += __shfl_xor(a, 32); return a; }
; DI void a_desc(int ti, int a0, int rho, int& tokbase, int& stride, int& maxd) {
;     if (ti < 4) { stride = 16; tokbase = rho + 512 * ti; maxd = 1024; }
;     else if (ti < 10) { stride = 4; const int m0 = 4 * a0 + (rho >> 2) - 64 + 32 * (ti - 4); tokbase = 4 * m0 + (rho & 3); maxd = 256; }
;     else { stride = 1; tokbase = 16 * a0 + rho - 64 + 32 * (ti - 10); maxd = 64; }
; }
; template <bool EDGE>
; DI void a_scores(f32x4 (&st)[2], const LAS char* kt, const bf16x8 (&qf)[2], const f32x4 cinit, int tokbase, int stride, int maxd, int tq, float nslope2, int lane) {
;     const int g = lane >> 4;
;     const int base0 = tokbase + stride * 4 * g - tq;
; #pragma unroll
;     for (int t = 0; t < 2; ++t) {
;         st[t] = MFMA16(k_frag_at(kt, t, 0, lane), qf[0], cinit); st[t] = MFMA16(k_frag_at(kt, t, 1, lane), qf[1], st[t]);
; #pragma unroll
;         for (int i = 0; i < 4; ++i) { const int d = base0 + stride * (16 * t + i);
;             bool ok = (unsigned)(d + maxd) <= (unsigned)(2 * maxd);
;             if (EDGE) ok = ok && ((unsigned)(d + tq) < (unsigned)T);
;             const float v = __builtin_fmaf(__builtin_fabsf((float)d), nslope2, st[t][i]);
;             st[t][i] = ok ? v : -1e30f; }
;     }
; }
; DI void a_stage(f32x4 (&st)[2], const TileRegs& R, LAS char* vt, int vpar, const bf16x8 (&qf)[2], const f32x4 cinit, int tokbase, int stride, int maxd, int tq, float nslope2, int lane) {
; #pragma unroll
;     for (int it = 0; it < 4; ++it) { const int n = lane + 64 * it, row = n >> 3, ch = n & 7;
	v_mfma_f32_16x16x32_bf16 v[16:19], v[36:39], v[4:7], v[16:19]
	v_cvt_f32_i32_e32 v37, v53
	v_add_u32_e32 v36, 64, v53
	v_cmp_gt_u32_e64 s[0:1], s73, v36
	v_add_u32_e32 v36, 1, v53
	s_cselect_b64 s[38:39], -1, 0
	v_cvt_f32_i32_e32 v36, v36
	s_nop 1
	v_fma_f32 v16, |v37|, v111, v16
	s_and_b64 s[0:1], s[38:39], s[0:1]
	v_lshlrev_b32_e32 v188, 7, v44
	v_cndmask_b32_e64 v162, v234, v16, s[0:1]
	v_add_u32_e32 v16, 0x41, v53
	v_lshl_add_u64 v[44:45], v[120:121], 0, v[188:189]
	v_cmp_gt_u32_e64 s[0:1], s73, v16
	v_lshl_add_u64 v[46:47], v[122:123], 0, v[188:189]
	global_load_dwordx4 v[92:95], v[44:45], off
	global_load_dwordx4 v[96:99], v[46:47], off
	v_fma_f32 v16, |v36|, v111, v17
	s_and_b64 s[0:1], s[38:39], s[0:1]
	ds_read_b128 v[36:39], v143 offset:11520
	ds_read_b128 v[44:47], v143 offset:11584
	v_cndmask_b32_e64 v163, v234, v16, s[0:1]
	v_add_u32_e32 v16, 2, v53
	v_cvt_f32_i32_e32 v16, v16
	v_add_u32_e32 v17, 0x42, v53
	v_cmp_gt_u32_e64 s[0:1], s73, v17
	s_and_b64 s[0:1], s[38:39], s[0:1]
	v_fma_f32 v16, |v16|, v111, v18
	v_cndmask_b32_e64 v164, v234, v16, s[0:1]
	v_add_u32_e32 v16, 3, v53
	v_cvt_f32_i32_e32 v16, v16
	s_waitcnt lgkmcnt(1)
	v_mfma_f32_16x16x32_bf16 v[36:39], v[36:39], v[8:11], v[12:15]
	v_add_u32_e32 v17, 0x43, v53
	v_cmp_gt_u32_e64 s[0:1], s73, v17
	v_fma_f32 v16, |v16|, v111, v19
	s_and_b64 s[0:1], s[38:39], s[0:1]
	v_cndmask_b32_e64 v165, v234, v16, s[0:1]
	s_waitcnt lgkmcnt(0)
	v_mfma_f32_16x16x32_bf16 v[16:19], v[44:47], v[4:7], v[36:39]
	s_add_i32 s31, s30, -16
	s_cmpk_lt_u32 s31, 0x800
	s_cselect_b64 s[38:39], -1, 0
	v_add_u32_e32 v36, 16, v53
	v_cvt_f32_i32_e32 v36, v36
	v_add_u32_e32 v37, 0x50, v53
	v_cmp_gt_u32_e64 s[0:1], s73, v37
	s_and_b64 s[0:1], s[38:39], s[0:1]
	v_fma_f32 v16, |v36|, v111, v16
	v_cndmask_b32_e64 v166, v234, v16, s[0:1]
	v_add_u32_e32 v16, 17, v53
	v_cvt_f32_i32_e32 v16, v16
	v_add_u32_e32 v36, 0x51, v53
	v_cmp_gt_u32_e64 s[0:1], s73, v36
	v_add_u32_e32 v36, 17, v52
	v_cmp_gt_u32_e64 s[38:39], s24, v36
	v_fma_f32 v16, |v16|, v111, v17
	s_and_b64 s[0:1], s[0:1], s[38:39]
	v_cndmask_b32_e64 v167, v234, v16, s[0:1]
	v_add_u32_e32 v16, 18, v53
	v_cvt_f32_i32_e32 v16, v16
	v_add_u32_e32 v17, 0x52, v53
	v_cmp_gt_u32_e64 s[0:1], s73, v17
	v_add_u32_e32 v17, 18, v52
	v_cmp_gt_u32_e64 s[38:39], s24, v17
	v_fma_f32 v16, |v16|, v111, v18
	s_and_b64 s[0:1], s[0:1], s[38:39]
	v_cndmask_b32_e64 v168, v234, v16, s[0:1]
	v_add_u32_e32 v16, 19, v53
	v_cvt_f32_i32_e32 v16, v16
	v_add_u32_e32 v17, 0x53, v53
	v_cmp_gt_u32_e64 s[0:1], s73, v17
	v_add_u32_e32 v17, 19, v52
	v_cmp_gt_u32_e64 s[38:39], s24, v17
	v_fma_f32 v16, |v16|, v111, v19
	s_and_b64 s[0:1], s[0:1], s[38:39]
	s_add_i32 s31, s30, 64
	v_cndmask_b32_e64 v169, v234, v16, s[0:1]
	v_or_b32_e32 v16, s31, v126
	v_med3_i32 v16, v16, 0, v233
	v_lshlrev_b32_e32 v188, 7, v16
	v_lshl_add_u64 v[16:17], v[120:121], 0, v[188:189]
	v_lshl_add_u64 v[18:19], v[122:123], 0, v[188:189]
	global_load_dwordx4 v[36:39], v[16:17], off
	global_load_dwordx4 v[44:47], v[18:19], off
	v_or_b32_e32 v16, s31, v127
	v_med3_i32 v16, v16, 0, v233
	v_lshlrev_b32_e32 v188, 7, v16
	v_lshl_add_u64 v[16:17], v[120:121], 0, v[188:189]
	v_lshl_add_u64 v[18:19], v[122:123], 0, v[188:189]
	global_load_dwordx4 v[52:55], v[16:17], off
	global_load_dwordx4 v[60:63], v[18:19], off
	v_add_u32_e32 v16, s31, v128
	v_med3_i32 v16, v16, 0, v233
	v_lshlrev_b32_e32 v188, 7, v16
	v_exp_f32_e32 v16, v113
	v_exp_f32_e32 v17, v115
	v_exp_f32_e32 v100, v117
	v_exp_f32_e32 v101, v119
	v_exp_f32_e32 v18, v154
	v_exp_f32_e32 v19, v155
	v_exp_f32_e32 v106, v156
	v_exp_f32_e32 v107, v157
	v_cvt_pk_bf16_f32 v16, v16, v17
	v_cvt_pk_bf16_f32 v17, v100, v101
	ds_read_b64_tr_b16 v[102:103], v144 offset:2304
	ds_read_b64_tr_b16 v[100:101], v144
	v_lshl_add_u64 v[104:105], v[120:121], 0, v[188:189]
	v_cvt_pk_bf16_f32 v18, v18, v19
	v_cvt_pk_bf16_f32 v19, v106, v107
	v_lshl_add_u64 v[106:107], v[122:123], 0, v[188:189]
	ds_read_b64_tr_b16 v[148:149], v144 offset:2336
	ds_read_b64_tr_b16 v[146:147], v144 offset:32
	ds_read_b64_tr_b16 v[150:151], v144 offset:64
	ds_read_b64_tr_b16 v[154:155], v144 offset:96
	ds_read_b64_tr_b16 v[152:153], v144 offset:2368
	ds_read_b64_tr_b16 v[156:157], v144 offset:2400
	s_waitcnt lgkmcnt(6)
	v_mfma_f32_16x16x32_bf16 v[158:161], v[100:103], v[16:19], 0
	global_load_dwordx4 v[100:103], v[104:105], off
	s_nop 0
	global_load_dwordx4 v[104:107], v[106:107], off
	s_waitcnt vmcnt(20)
	ds_write_b128 v142, v[24:27]
	ds_write_b128 v142, v[20:23] offset:9216
	s_waitcnt vmcnt(18)
	ds_write_b128 v142, v[32:35] offset:1152
	ds_write_b128 v142, v[28:31] offset:10368
	s_waitcnt vmcnt(16)
	ds_write_b128 v142, v[48:51] offset:2304
	ds_write_b128 v142, v[40:43] offset:11520
	s_waitcnt vmcnt(14)
	ds_write_b128 v142, v[64:67] offset:3456
	ds_write_b128 v142, v[56:59] offset:12672
	ds_read_b128 v[20:23], v143 offset:9216
	ds_read_b128 v[40:43], v143 offset:9280
	v_add_u32_e32 v28, s31, v129
	v_med3_i32 v28, v28, 0, v233
	v_lshlrev_b32_e32 v188, 7, v28
	v_lshl_add_u64 v[28:29], v[120:121], 0, v[188:189]
	v_lshl_add_u64 v[32:33], v[122:123], 0, v[188:189]
	global_load_dwordx4 v[28:31], v[28:29], off
	s_nop 0
	global_load_dwordx4 v[32:35], v[32:33], off
	s_waitcnt lgkmcnt(1)
	v_mfma_f32_16x16x32_bf16 v[20:23], v[20:23], v[8:11], v[12:15]
	ds_read_b128 v[56:59], v143 offset:11584
	s_cmpk_lt_u32 s30, 0x800
	s_cselect_b64 s[0:1], -1, 0
	s_waitcnt lgkmcnt(1)
	v_mfma_f32_16x16x32_bf16 v[20:23], v[40:43], v[4:7], v[20:23]
	ds_read_b128 v[40:43], v143 offset:11520
	v_exp_f32_e32 v64, v168
	v_exp_f32_e32 v65, v169
	s_waitcnt lgkmcnt(0)
; DI void fb_update(f32x4 (&o)[4], f32x4& ol, const f32x4 st0, const f32x4 st1, const LAS char* vt, int lane) {
;     f32x4 p0, p1;
; #pragma unroll
;     for (int i = 0; i < 4; ++i) { p0[i] = ex2(st0[i]); p1[i] = ex2(st1[i]); }
;     const bf16x8 pf = pack8(p0, p1);
;     const bf16x8 ones = {0x3F80, 0x3F80, 0x3F80, 0x3F80, 0x3F80, 0x3F80, 0x3F80, 0x3F80};
;     ol = MFMA16(ones, pf, ol);
;     const int g = lane >> 4, q = (lane & 15) >> 2, p = lane & 3;
;     const LAS char* v0 = vt + (4 * g + q) * VT_PITCH + 8 * p;
;     const LAS char* v1 = v0 + 16 * VT_PITCH;
; #pragma unroll
;     for (int c = 0; c < 4; ++c) { const bf16x8 vf = cat8(vtr(v0 + 32 * c), vtr(v1 + 32 * c)); o[c] = MFMA16(vf, pf, o[c]); }
; }
; DI float q_norm2(const bf16x8 (&qf)[2]) { float a = sumsq8(qf[0]) + sumsq8(qf[1]); a += __shfl_xor(a, 16); a += __shfl_xor(a, 32); return a; }
; DI void a_desc(int ti, int a0, int rho, int& tokbase, int& stride, int& maxd) {
;     if (ti < 4) { stride = 16; tokbase = rho + 512 * ti; maxd = 1024; }
;     else if (ti < 10) { stride = 4; const int m0 = 4 * a0 + (rho >> 2) - 64 + 32 * (ti - 4); tokbase = 4 * m0 + (rho & 3); maxd = 256; }
;     else { stride = 1; tokbase = 16 * a0 + rho - 64 + 32 * (ti - 10); maxd = 64; }
; }
; template <bool EDGE>
; DI void a_scores(f32x4 (&st)[2], const LAS char* kt, const bf16x8 (&qf)[2], const f32x4 cinit, int tokbase, int stride, int maxd, int tq, float nslope2, int lane) {
;     const int g = lane >> 4;
;     const int base0 = tokbase + stride * 4 * g - tq;
; #pragma unroll
;     for (int t = 0; t < 2; ++t) {
;         st[t] = MFMA16(k_frag_at(kt, t, 0, lane), qf[0], cinit); st[t] = MFMA16(k_frag_at(kt, t, 1, lane), qf[1], st[t]);
; #pragma unroll
;         for (int i = 0; i < 4; ++i) { const int d = base0 + stride * (16 * t + i);
;             bool ok = (unsigned)(d + maxd) <= (unsigned)(2 * maxd);
;             if (EDGE) ok = ok && ((unsigned)(d + tq) < (unsigned)T);
;             const float v = __builtin_fmaf(__builtin_fabsf((float)d), nslope2, st[t][i]);
;             st[t][i] = ok ? v : -1e30f; }
;     }
; }
; DI void a_stage(f32x4 (&st)[2], const TileRegs& R, LAS char* vt, int vpar, const bf16x8 (&qf)[2], const f32x4 cinit, int tokbase, int stride, int maxd, int tq, float nslope2, int lane) {
; #pragma unroll
;     for (int it = 0; it < 4; ++it) { const int n = lane + 64 * it, row = n >> 3, ch = n & 7;
	v_mfma_f32_16x16x32_bf16 v[40:43], v[40:43], v[8:11], v[12:15]
	s_nop 2
	v_fma_f32 v20, |v133|, v111, v20
	v_cndmask_b32_e64 v115, v234, v20, s[0:1]
	v_fma_f32 v20, |v134|, v111, v21
	v_cndmask_b32_e64 v117, v234, v20, s[0:1]
	v_fma_f32 v20, |v135|, v111, v22
	v_cndmask_b32_e64 v119, v234, v20, s[0:1]
	v_fma_f32 v20, |v136|, v111, v23
	v_mfma_f32_16x16x32_bf16 v[48:51], v[154:157], v[16:19], 0
	v_cndmask_b32_e64 v154, v234, v20, s[0:1]
	v_exp_f32_e32 v20, v162
	v_exp_f32_e32 v22, v166
	v_mfma_f32_16x16x32_bf16 v[40:43], v[56:59], v[4:7], v[40:43]
	v_exp_f32_e32 v21, v163
	v_exp_f32_e32 v23, v167
	v_exp_f32_e32 v56, v164
	v_exp_f32_e32 v57, v165
	v_mfma_f32_16x16x32_bf16 v[24:27], v[150:153], v[16:19], 0
	v_cvt_pk_bf16_f32 v20, v20, v21
	v_cvt_pk_bf16_f32 v22, v22, v23
	v_cvt_pk_bf16_f32 v21, v56, v57
	ds_read_b64_tr_b16 v[58:59], v144 offset:6912
	ds_read_b64_tr_b16 v[56:57], v144 offset:4608
	v_cvt_pk_bf16_f32 v23, v64, v65
	ds_read_b64_tr_b16 v[66:67], v144 offset:6944
	ds_read_b64_tr_b16 v[64:65], v144 offset:4640
	ds_read_b64_tr_b16 v[120:121], v144 offset:4672
	ds_read_b64_tr_b16 v[150:151], v144 offset:4704
	ds_read_b64_tr_b16 v[122:123], v144 offset:6976
	ds_read_b64_tr_b16 v[152:153], v144 offset:7008
	s_waitcnt vmcnt(14)
	ds_write_b128 v142, v[72:75] offset:4608
	ds_write_b128 v142, v[68:71] offset:9216
	s_waitcnt vmcnt(12)
	ds_write_b128 v142, v[80:83] offset:5760
	ds_write_b128 v142, v[76:79] offset:10368
	s_waitcnt vmcnt(10)
	ds_write_b128 v142, v[88:91] offset:6912
	ds_write_b128 v142, v[84:87] offset:11520
	s_waitcnt vmcnt(8)
	ds_write_b128 v142, v[96:99] offset:8064
	ds_write_b128 v142, v[92:95] offset:12672
	s_waitcnt lgkmcnt(9)
	v_mfma_f32_16x16x32_bf16 v[120:123], v[120:123], v[20:23], v[24:27]
	ds_read_b128 v[68:71], v143 offset:9280
	s_nop 1
	ds_read_b128 v[24:27], v143 offset:9216
	s_add_i32 s0, s30, 16
	v_mfma_f32_16x16x32_bf16 v[146:149], v[146:149], v[16:19], 0
	s_cmpk_lt_u32 s0, 0x800
	v_or_b32_e32 v113, s30, v131
	v_fma_f32 v40, v137, v111, v40
	s_cselect_b64 s[0:1], -1, 0
	s_waitcnt lgkmcnt(0)
	v_mfma_f32_16x16x32_bf16 v[24:27], v[24:27], v[8:11], v[12:15]
	v_cndmask_b32_e64 v155, v234, v40, s[0:1]
	v_add_u32_e32 v40, 17, v113
	v_fma_f32 v41, v138, v111, v41
	v_cmp_gt_u32_e64 s[0:1], s24, v40
	v_add_u32_e32 v40, 18, v113
	v_or_b32_e32 v84, s33, v131
	v_mfma_f32_16x16x32_bf16 v[64:67], v[64:67], v[20:23], v[146:149]
	v_sub_u32_e32 v85, v84, v114
	v_fmac_f32_e32 v43, v140, v111
	s_cmpk_lt_u32 s33, 0x800
	v_cndmask_b32_e64 v146, v234, v41, s[0:1]
	v_fma_f32 v41, v139, v111, v42
	v_cmp_gt_u32_e64 s[0:1], s24, v40
	v_add_u32_e32 v40, 19, v113
	v_mfma_f32_16x16x32_bf16 v[24:27], v[68:71], v[4:7], v[24:27]
	v_cndmask_b32_e64 v72, v234, v41, s[0:1]
	v_cvt_f32_i32_e32 v41, v85
	v_cmp_gt_u32_e64 s[0:1], s24, v40
	v_add_u32_e32 v40, 64, v85
	s_cselect_b64 s[38:39], -1, 0
	v_cndmask_b32_e64 v73, v234, v43, s[0:1]
	v_cmp_gt_u32_e64 s[0:1], s73, v40
	v_add_u32_e32 v40, 1, v85
	v_cvt_f32_i32_e32 v40, v40
	v_fma_f32 v24, |v41|, v111, v24
	s_and_b64 s[0:1], s[38:39], s[0:1]
	v_cndmask_b32_e64 v86, v234, v24, s[0:1]
	v_add_u32_e32 v24, 0x41, v85
	v_cmp_gt_u32_e64 s[0:1], s73, v24
	v_fma_f32 v24, |v40|, v111, v25
	s_and_b64 s[0:1], s[38:39], s[0:1]
	v_cndmask_b32_e64 v87, v234, v24, s[0:1]
	v_add_u32_e32 v24, 2, v85
	ds_read_b128 v[40:43], v143 offset:11520
	ds_read_b128 v[68:71], v143 offset:11584
	v_cvt_f32_i32_e32 v24, v24
	v_add_u32_e32 v25, 0x42, v85
	v_cmp_gt_u32_e64 s[0:1], s73, v25
	s_and_b64 s[0:1], s[38:39], s[0:1]
	v_fma_f32 v24, |v24|, v111, v26
	v_cndmask_b32_e64 v88, v234, v24, s[0:1]
	v_add_u32_e32 v24, 3, v85
	v_cvt_f32_i32_e32 v24, v24
	v_add_u32_e32 v25, 0x43, v85
	s_waitcnt lgkmcnt(1)
	v_mfma_f32_16x16x32_bf16 v[40:43], v[40:43], v[8:11], v[12:15]
	v_cmp_gt_u32_e64 s[0:1], s73, v25
	v_fma_f32 v24, |v24|, v111, v27
	s_and_b64 s[0:1], s[38:39], s[0:1]
	v_cndmask_b32_e64 v89, v234, v24, s[0:1]
	v_add_u32_e32 v24, 16, v85
	s_waitcnt lgkmcnt(0)
	v_mfma_f32_16x16x32_bf16 v[40:43], v[68:71], v[4:7], v[40:43]
	v_cvt_f32_i32_e32 v24, v24
	s_add_i32 s33, s30, 48
	v_add_u32_e32 v25, 0x50, v85
	s_cmpk_lt_u32 s33, 0x800
	v_cmp_gt_u32_e64 s[0:1], s73, v25
	s_cselect_b64 s[38:39], -1, 0
	s_nop 1
	v_fma_f32 v24, |v24|, v111, v40
	s_and_b64 s[0:1], s[38:39], s[0:1]
	v_cndmask_b32_e64 v90, v234, v24, s[0:1]
	v_add_u32_e32 v24, 17, v85
	v_cvt_f32_i32_e32 v24, v24
	v_add_u32_e32 v25, 0x51, v85
	v_cmp_gt_u32_e64 s[0:1], s73, v25
	v_add_u32_e32 v25, 17, v84
	v_cmp_gt_u32_e64 s[38:39], s24, v25
	v_fma_f32 v24, |v24|, v111, v41
	s_and_b64 s[0:1], s[0:1], s[38:39]
	v_cndmask_b32_e64 v91, v234, v24, s[0:1]
	v_add_u32_e32 v24, 18, v85
	v_add_u32_e32 v25, 0x52, v85
	v_cmp_gt_u32_e64 s[0:1], s73, v25
	v_cvt_f32_i32_e32 v40, v24
	v_exp_f32_e32 v24, v115
	v_exp_f32_e32 v26, v155
	v_exp_f32_e32 v25, v117
	v_exp_f32_e32 v27, v146
	v_exp_f32_e32 v41, v119
	v_exp_f32_e32 v68, v154
	v_exp_f32_e32 v72, v72
	v_exp_f32_e32 v73, v73
	v_cvt_pk_bf16_f32 v24, v24, v25
	v_cvt_pk_bf16_f32 v25, v41, v68
	ds_read_b64_tr_b16 v[70:71], v144 offset:2304
	ds_read_b64_tr_b16 v[68:69], v144
	v_cvt_pk_bf16_f32 v26, v26, v27
	v_cvt_pk_bf16_f32 v27, v72, v73
	ds_read_b64_tr_b16 v[74:75], v144 offset:2336
	ds_read_b64_tr_b16 v[72:73], v144 offset:32
	ds_read_b64_tr_b16 v[76:77], v144 offset:64
	ds_read_b64_tr_b16 v[80:81], v144 offset:96
	ds_read_b64_tr_b16 v[78:79], v144 offset:2368
	ds_read_b64_tr_b16 v[82:83], v144 offset:2400
	s_waitcnt vmcnt(6)
	ds_write_b128 v142, v[44:47]
	ds_write_b128 v142, v[36:39] offset:9216
	s_waitcnt vmcnt(4)
	ds_write_b128 v142, v[60:63] offset:1152
	ds_write_b128 v142, v[52:55] offset:10368
	s_waitcnt vmcnt(2)
; DI void fb_update(f32x4 (&o)[4], f32x4& ol, const f32x4 st0, const f32x4 st1, const LAS char* vt, int lane) {
;     f32x4 p0, p1;
; #pragma unroll
;     for (int i = 0; i < 4; ++i) { p0[i] = ex2(st0[i]); p1[i] = ex2(st1[i]); }
;     const bf16x8 pf = pack8(p0, p1);
;     const bf16x8 ones = {0x3F80, 0x3F80, 0x3F80, 0x3F80, 0x3F80, 0x3F80, 0x3F80, 0x3F80};
;     ol = MFMA16(ones, pf, ol);
;     const int g = lane >> 4, q = (lane & 15) >> 2, p = lane & 3;
;     const LAS char* v0 = vt + (4 * g + q) * VT_PITCH + 8 * p;
;     const LAS char* v1 = v0 + 16 * VT_PITCH;
; #pragma unroll
;     for (int c = 0; c < 4; ++c) { const bf16x8 vf = cat8(vtr(v0 + 32 * c), vtr(v1 + 32 * c)); o[c] = MFMA16(vf, pf, o[c]); }
; }
; DI float q_norm2(const bf16x8 (&qf)[2]) { float a = sumsq8(qf[0]) + sumsq8(qf[1]); a += __shfl_xor(a, 16); a += __shfl_xor(a, 32); return a; }
; DI void a_desc(int ti, int a0, int rho, int& tokbase, int& stride, int& maxd) {
;     if (ti < 4) { stride = 16; tokbase = rho + 512 * ti; maxd = 1024; }
;     else if (ti < 10) { stride = 4; const int m0 = 4 * a0 + (rho >> 2) - 64 + 32 * (ti - 4); tokbase = 4 * m0 + (rho & 3); maxd = 256; }
;     else { stride = 1; tokbase = 16 * a0 + rho - 64 + 32 * (ti - 10); maxd = 64; }
; }
; template <bool EDGE>
; DI void a_scores(f32x4 (&st)[2], const LAS char* kt, const bf16x8 (&qf)[2], const f32x4 cinit, int tokbase, int stride, int maxd, int tq, float nslope2, int lane) {
;     const int g = lane >> 4;
;     const int base0 = tokbase + stride * 4 * g - tq;
; #pragma unroll
;     for (int t = 0; t < 2; ++t) {
;         st[t] = MFMA16(k_frag_at(kt, t, 0, lane), qf[0], cinit); st[t] = MFMA16(k_frag_at(kt, t, 1, lane), qf[1], st[t]);
; #pragma unroll
;         for (int i = 0; i < 4; ++i) { const int d = base0 + stride * (16 * t + i);
;             bool ok = (unsigned)(d + maxd) <= (unsigned)(2 * maxd);
;             if (EDGE) ok = ok && ((unsigned)(d + tq) < (unsigned)T);
;             const float v = __builtin_fmaf(__builtin_fabsf((float)d), nslope2, st[t][i]);
;             st[t][i] = ok ? v : -1e30f; }
;     }
; }
; DI void a_stage(f32x4 (&st)[2], const TileRegs& R, LAS char* vt, int vpar, const bf16x8 (&qf)[2], const f32x4 cinit, int tokbase, int stride, int maxd, int tq, float nslope2, int lane) {
; #pragma unroll
;     for (int it = 0; it < 4; ++it) { const int n = lane + 64 * it, row = n >> 3, ch = n & 7;
	ds_write_b128 v142, v[104:107] offset:2304
	ds_write_b128 v142, v[100:103] offset:11520
	s_waitcnt vmcnt(0)
	ds_write_b128 v142, v[32:35] offset:3456
	ds_write_b128 v142, v[28:31] offset:12672
	ds_read_b128 v[28:31], v143 offset:9216
	ds_read_b128 v[36:39], v143 offset:9280
	v_add_u32_e32 v41, 18, v84
	v_cmp_gt_u32_e64 s[38:39], s24, v41
	v_fma_f32 v40, |v40|, v111, v42
	s_and_b64 s[0:1], s[0:1], s[38:39]
	s_waitcnt lgkmcnt(14)
	v_mfma_f32_16x16x32_bf16 v[64:67], v[72:75], v[24:27], v[64:67]
	v_cndmask_b32_e64 v72, v234, v40, s[0:1]
	v_add_u32_e32 v40, 19, v85
	v_cvt_f32_i32_e32 v40, v40
	s_waitcnt lgkmcnt(1)
	v_mfma_f32_16x16x32_bf16 v[28:31], v[28:31], v[8:11], v[12:15]
	v_add_u32_e32 v32, 0x53, v85
	v_add_u32_e32 v41, 19, v84
	v_or_b32_e32 v45, s31, v131
	v_cmp_gt_u32_e64 s[0:1], s73, v32
	v_cmp_gt_u32_e64 s[38:39], s24, v41
	v_sub_u32_e32 v46, v45, v114
	v_fma_f32 v40, |v40|, v111, v43
	s_and_b64 s[0:1], s[0:1], s[38:39]
	s_waitcnt lgkmcnt(0)
	v_mfma_f32_16x16x32_bf16 v[28:31], v[36:39], v[4:7], v[28:31]
	v_add_u32_e32 v36, 64, v46
	v_cvt_f32_i32_e32 v37, v46
	v_cndmask_b32_e64 v44, v234, v40, s[0:1]
	v_cmp_gt_u32_e64 s[0:1], s73, v36
	v_add_u32_e32 v36, 1, v46
	s_cmpk_lt_u32 s31, 0x800
	v_cvt_f32_i32_e32 v36, v36
	s_cselect_b64 s[38:39], -1, 0
	v_fma_f32 v28, |v37|, v111, v28
	s_and_b64 s[0:1], s[38:39], s[0:1]
	v_cndmask_b32_e64 v47, v234, v28, s[0:1]
	v_add_u32_e32 v28, 0x41, v46
	v_cmp_gt_u32_e64 s[0:1], s73, v28
	v_fma_f32 v28, |v36|, v111, v29
	ds_read_b128 v[36:39], v143 offset:11520
	ds_read_b128 v[40:43], v143 offset:11584
	v_mfma_f32_16x16x32_bf16 v[48:51], v[150:153], v[20:23], v[48:51]
	s_and_b64 s[0:1], s[38:39], s[0:1]
	v_add_u32_e32 v29, 0x42, v46
	s_addk_i32 s30, 0x50
	v_mfma_f32_16x16x32_bf16 v[32:35], v[80:83], v[24:27], v[48:51]
	v_mov_b32_e32 v113, v189
	v_ashrrev_i32_e32 v117, 31, v116
	v_ashrrev_i32_e32 v119, 31, v118
	s_nop 0
	v_cndmask_b32_e64 v48, v234, v28, s[0:1]
	v_add_u32_e32 v28, 2, v46
	v_cvt_f32_i32_e32 v28, v28
	v_cmp_gt_u32_e64 s[0:1], s73, v29
	s_waitcnt lgkmcnt(1)
	v_mfma_f32_16x16x32_bf16 v[8:11], v[36:39], v[8:11], v[12:15]
	s_and_b64 s[0:1], s[38:39], s[0:1]
	v_fma_f32 v28, |v28|, v111, v30
	v_cndmask_b32_e64 v49, v234, v28, s[0:1]
	v_add_u32_e32 v28, 3, v46
	v_cvt_f32_i32_e32 v28, v28
	v_add_u32_e32 v29, 0x43, v46
	s_waitcnt lgkmcnt(0)
	v_mfma_f32_16x16x32_bf16 v[4:7], v[40:43], v[4:7], v[8:11]
	v_cmp_gt_u32_e64 s[0:1], s73, v29
	s_and_b64 s[0:1], s[38:39], s[0:1]
	v_fma_f32 v12, |v28|, v111, v31
	v_add_u32_e32 v8, 16, v46
	v_cvt_f32_i32_e32 v8, v8
	v_add_u32_e32 v9, 0x50, v46
	s_cmpk_lt_u32 s30, 0x800
	v_cndmask_b32_e64 v50, v234, v12, s[0:1]
	v_cmp_gt_u32_e64 s[0:1], s73, v9
	s_cselect_b64 s[30:31], -1, 0
	v_fma_f32 v4, |v8|, v111, v4
	s_and_b64 s[0:1], s[30:31], s[0:1]
	v_cndmask_b32_e64 v51, v234, v4, s[0:1]
	v_add_u32_e32 v4, 17, v46
	v_cvt_f32_i32_e32 v4, v4
	v_add_u32_e32 v8, 0x51, v46
	v_cmp_gt_u32_e64 s[0:1], s73, v8
	v_add_u32_e32 v8, 17, v45
	v_cmp_gt_u32_e64 s[38:39], s24, v8
	v_fma_f32 v4, |v4|, v111, v5
	s_and_b64 s[0:1], s[0:1], s[38:39]
	v_cndmask_b32_e64 v52, v234, v4, s[0:1]
	v_add_u32_e32 v4, 18, v46
	v_cvt_f32_i32_e32 v4, v4
	v_add_u32_e32 v5, 0x52, v46
	v_cmp_gt_u32_e64 s[0:1], s73, v5
	v_add_u32_e32 v5, 18, v45
	v_cmp_gt_u32_e64 s[38:39], s24, v5
	v_fma_f32 v4, |v4|, v111, v6
	s_and_b64 s[0:1], s[0:1], s[38:39]
	v_cndmask_b32_e64 v53, v234, v4, s[0:1]
	v_exp_f32_e32 v4, v86
	v_exp_f32_e32 v6, v87
	v_exp_f32_e32 v9, v88
	v_exp_f32_e32 v11, v89
	v_exp_f32_e32 v28, v72
	v_exp_f32_e32 v29, v44
	v_exp_f32_e32 v5, v90
	v_exp_f32_e32 v10, v91
	v_cvt_pk_bf16_f32 v8, v4, v6
	v_add_u32_e32 v4, 19, v46
	v_cvt_pk_bf16_f32 v9, v9, v11
	ds_read_b64_tr_b16 v[12:13], v144 offset:4608
	ds_read_b64_tr_b16 v[14:15], v144 offset:6912
	v_cvt_pk_bf16_f32 v11, v28, v29
	ds_read_b64_tr_b16 v[30:31], v144 offset:6944
	ds_read_b64_tr_b16 v[28:29], v144 offset:4640
	ds_read_b64_tr_b16 v[36:37], v144 offset:4672
	ds_read_b64_tr_b16 v[40:41], v144 offset:4704
	ds_read_b64_tr_b16 v[38:39], v144 offset:6976
	ds_read_b64_tr_b16 v[42:43], v144 offset:7008
	v_cvt_f32_i32_e32 v4, v4
	v_cvt_pk_bf16_f32 v10, v5, v10
	v_add_u32_e32 v5, 0x53, v46
	v_mfma_f32_16x16x32_bf16 v[56:59], v[56:59], v[20:23], v[158:161]
	v_cmp_gt_u32_e64 s[0:1], s73, v5
	v_add_u32_e32 v5, 19, v45
	v_cmp_gt_u32_e64 s[38:39], s24, v5
	v_fma_f32 v4, |v4|, v111, v7
	s_and_b64 s[0:1], s[0:1], s[38:39]
	v_cndmask_b32_e64 v44, v234, v4, s[0:1]
	s_waitcnt lgkmcnt(0)
; #define LAS __attribute__((address_space(3)))
; #define MFMA16(a, b, c) __builtin_amdgcn_mfma_f32_16x16x32_bf16((a), (b), (c), 0, 0, 0)
; DI unsigned pk2(float lo, float hi) { f32x2_t v = {lo, hi}; bf16x2_t b = __builtin_convertvector(v, bf16x2_t); return __builtin_bit_cast(unsigned, b); }
; DI float ex2(float x) { return __builtin_amdgcn_exp2f(x); }
; DI s16x4 vtr(const LAS char* p) { return __builtin_bit_cast(s16x4, __builtin_amdgcn_ds_read_tr16_b64_v4i16((LAS s16x4*)p)); }
; DI bf16x8 cat8(s16x4 lo, s16x4 hi) { return __builtin_shufflevector(lo, hi, 0, 1, 2, 3, 4, 5, 6, 7); }
; DI bf16x8 pack8(f32x4 a, f32x4 b) { u32x4 w; w.x = pk2(a[0], a[1]); w.y = pk2(a[2], a[3]); w.z = pk2(b[0], b[1]); w.w = pk2(b[2], b[3]); return __builtin_bit_cast(bf16x8, w); }
; DI void fb_update(f32x4 (&o)[4], f32x4& ol, const f32x4 st0, const f32x4 st1, const LAS char* vt, int lane) {
;     ...
;     for (int i = 0; i < 4; ++i) { p0[i] = ex2(st0[i]); p1[i] = ex2(st1[i]); }
;     const bf16x8 pf = pack8(p0, p1);
;     const bf16x8 ones = {0x3F80, 0x3F80, 0x3F80, 0x3F80, 0x3F80, 0x3F80, 0x3F80, 0x3F80};
;     ol = MFMA16(ones, pf, ol);
;     const int g = lane >> 4, q = (lane & 15) >> 2, p = lane & 3;
;     const LAS char* v0 = vt + (4 * g + q) * VT_PITCH + 8 * p;
;     const LAS char* v1 = v0 + 16 * VT_PITCH;
; #pragma unroll
;     for (int c = 0; c < 4; ++c) { const bf16x8 vf = cat8(vtr(v0 + 32 * c), vtr(v1 + 32 * c)); o[c] = MFMA16(vf, pf, o[c]); }
; DI void mixerA1_unit(int u, const bf16* PROJ, bf16* YC, float* LPA, const float* kmax_l, LAS char* vt, int wave, int lane) {
;     ...
;     LAS char* sc = vt + SC_OFF;
; #pragma unroll
;     for (int c = 0; c < 4; ++c) { u32x2 w; w.x = pk2(o[c][0], o[c][1]); w.y = pk2(o[c][2], o[c][3]);
;         *(LAS u32x2*)(sc + r * VT_PITCH + (16 * c + 4 * g) * 2) = w; }
;     rows16_store(sc, YC + (size_t)b * T * 1024 + h * 64, 1024, t0, 1, lane);
;     if (g == 0) LPA[(size_t)(b * T + tq) * 4 + h] = ol[0];
	v_mfma_f32_16x16x32_bf16 v[4:7], v[40:43], v[8:11], v[32:35]
	v_exp_f32_e32 v40, v49
	v_exp_f32_e32 v41, v50
	v_exp_f32_e32 v45, v53
	v_exp_f32_e32 v32, v47
	v_exp_f32_e32 v33, v48
	v_mfma_f32_16x16x32_bf16 v[56:59], v[68:71], v[24:27], v[56:59]
	v_exp_f32_e32 v34, v51
	v_exp_f32_e32 v35, v52
	v_exp_f32_e32 v44, v44
	v_cvt_pk_bf16_f32 v32, v32, v33
	v_cvt_pk_bf16_f32 v33, v40, v41
	ds_read_b64_tr_b16 v[42:43], v144 offset:2304
	ds_read_b64_tr_b16 v[40:41], v144
	v_mfma_f32_16x16x32_bf16 v[12:15], v[12:15], v[8:11], v[56:59]
	v_cvt_pk_bf16_f32 v34, v34, v35
	v_cvt_pk_bf16_f32 v35, v45, v44
	ds_read_b64_tr_b16 v[46:47], v144 offset:2336
	ds_read_b64_tr_b16 v[44:45], v144 offset:32
	ds_read_b64_tr_b16 v[48:49], v144 offset:64
	ds_read_b64_tr_b16 v[52:53], v144 offset:96
	ds_read_b64_tr_b16 v[50:51], v144 offset:2368
	ds_read_b64_tr_b16 v[54:55], v144 offset:2400
	s_waitcnt lgkmcnt(6)
	v_mfma_f32_16x16x32_bf16 v[12:15], v[40:43], v[32:35], v[12:15]
	v_mov_b64_e32 v[40:41], s[84:85]
	v_mov_b64_e32 v[42:43], s[86:87]
	s_lshl_b64 s[0:1], s[20:21], 22
	v_mfma_f32_16x16x32_bf16 v[28:31], v[28:31], v[8:11], v[64:67]
	s_add_u32 s0, s8, s0
	s_addc_u32 s1, s9, s1
	s_lshl_b32 s21, s27, 7
	v_mfma_f32_16x16x32_bf16 v[16:19], v[40:43], v[16:19], 0
	s_add_u32 s0, s0, s21
	s_addc_u32 s1, s1, 0
	v_mfma_f32_16x16x32_bf16 v[68:71], v[76:79], v[24:27], v[120:123]
	s_waitcnt lgkmcnt(4)
	v_mfma_f32_16x16x32_bf16 v[28:31], v[44:47], v[32:35], v[28:31]
	v_cvt_pk_bf16_f32 v44, v12, v13
	v_cvt_pk_bf16_f32 v45, v14, v15
	v_add_u32_e32 v46, v132, v108
	v_mfma_f32_16x16x32_bf16 v[12:15], v[40:43], v[20:23], v[16:19]
	v_mfma_f32_16x16x32_bf16 v[36:39], v[36:39], v[8:11], v[68:71]
	s_nop 2
	v_cvt_pk_bf16_f32 v16, v28, v29
	v_cvt_pk_bf16_f32 v17, v30, v31
	v_add_u32_e32 v18, 0x2000, v46
	v_mfma_f32_16x16x32_bf16 v[12:15], v[40:43], v[24:27], v[12:15]
	ds_write2_b64 v18, v[44:45], v[16:17] offset0:128 offset1:132
	s_waitcnt lgkmcnt(2)
	v_mfma_f32_16x16x32_bf16 v[36:39], v[48:51], v[32:35], v[36:39]
	s_waitcnt lgkmcnt(1)
	v_mfma_f32_16x16x32_bf16 v[4:7], v[52:55], v[32:35], v[4:7]
	v_mfma_f32_16x16x32_bf16 v[8:11], v[40:43], v[8:11], v[12:15]
	s_nop 4
	v_cvt_pk_bf16_f32 v16, v36, v37
	v_cvt_pk_bf16_f32 v17, v38, v39
	v_cvt_pk_bf16_f32 v4, v4, v5
	v_cvt_pk_bf16_f32 v5, v6, v7
	ds_write2_b64 v18, v[16:17], v[4:5] offset0:136 offset1:140
	v_mfma_f32_16x16x32_bf16 v[4:7], v[40:43], v[32:35], v[8:11]
	v_lshl_add_u64 v[14:15], s[0:1], 0, v[112:113]
	s_nop 1
	v_lshlrev_b64 v[10:11], 11, v[116:117]
	v_lshl_add_u64 v[16:17], v[14:15], 0, v[10:11]
	s_nop 2
	v_add_u32_e32 v5, v141, v130
	ds_read_b128 v[6:9], v5 offset:9216
	ds_read_b128 v[10:13], v145 offset:9216
	s_waitcnt lgkmcnt(1)
	global_store_dwordx4 v[16:17], v[6:9], off sc1
	s_nop 1
	v_lshlrev_b64 v[6:7], 11, v[118:119]
	v_lshl_add_u64 v[6:7], v[14:15], 0, v[6:7]
	s_waitcnt lgkmcnt(0)
	global_store_dwordx4 v[6:7], v[10:13], off sc1
	s_and_saveexec_b64 s[0:1], vcc
	s_cbranch_execz .LBB0_358
	v_lshl_add_u32 v6, s20, 11, v114
	v_ashrrev_i32_e32 v7, 31, v6
	v_lshl_add_u64 v[6:7], v[6:7], 4, s[96:97]
	s_lshl_b32 s34, s27, 2
	v_lshl_add_u64 v[6:7], v[6:7], 0, s[34:35]
	global_store_dword v[6:7], v4, off
	s_branch .LBB0_358
